# DIFF attention unit prologue: K/V loads of tiles 1 and 2 issued together with tile 0 and q (single exposed round trip)
# baseline (speedup 1.0000x reference)
; __device__ __forceinline__ int otid() { int t = threadIdx.x; asm volatile("" : "+v"(t)); return t; }
; __device__ __forceinline__ int v_st(int k, int c) { const int kk = (k & ~0xC) | ((k & 4) << 1) | ((k & 8) >> 1); return ((kk >> 3) * 4 + (c >> 5)) * 512 + ((kk & 7) * 32 + (c & 31)) * 2; }
; __device__ __forceinline__ int v_rd_base(int lane) { return ((lane & 3) << 3) | (((lane >> 2) & 3) << 6) | (((lane >> 4) & 1) << 5) | (((lane >> 5) & 1) << 8); }
; #define VM0() asm volatile("s_waitcnt vmcnt(0)" ::: "memory")
; #define WGBAR() asm volatile("s_waitcnt lgkmcnt(0)\n\ts_barrier" ::: "memory")
; template <int DQK, int KW, bool DIFF, int SDEPTH, int QSP, int NBUF>
; __device__ __forceinline__ void attn_unit(const UnitP& P, char* lds) {
;     ...
;   const int tid = otid(), wid = tid >> 6, lane = tid & 63, r32 = lane & 31, hi = lane >> 5;
;   char* V_lds = lds; char* K_lds = lds + NBUF * SHM_V;
;   float* ws = (float*)(lds + NBUF * (SHM_V + SHM_K)) + wid * 64; float* li_l = ws; float* al_l = ws + 32;
;   float m_reg = DIFF ? 0.f : -1e30f, l_reg = 0; f32x16 o[4] = {}; f32x16 negm = {}; if constexpr (DIFF) asm volatile("" : "+v"(negm));    constexpr int NQR = DQK / 16 - QSP; bf16x8 qr[NQR > 0 ? NQR : 1];
;   char* qsp = lds + NBUF * (SHM_V + SHM_K) + 2048 + wid * (QSP * 1024) + lane * 16;
;   const int coffB = DIFF ? (wid >> 2) * 128 : 0;
;   { const bf16_t* Qp = P.Qw + (long)r32 * P.ldq + hi * 8;
; #pragma unroll
;     for (int d0 = 0; d0 < NQR; ++d0) qr[d0] = *reinterpret_cast<const bf16x8*>(Qp + d0 * 16);
; #pragma unroll
;     for (int d0 = NQR; d0 < DQK / 16; ++d0) *reinterpret_cast<bf16x8*>(qsp + (d0 - NQR) * 1024) = *reinterpret_cast<const bf16x8*>(Qp + d0 * 16); }
;   const int sr = tid >> 4, sc = (tid & 15) * 8, vst0 = v_st(sr, sc), vst1 = v_st(32 + sr, sc);
;   const int vb0 = (int)(uintptr_t)V_lds + v_rd_base(lane);
;   int kb[4];
; #pragma unroll
;   for (int q = 0; q < 4; ++q) kb[q] = coffB + kswz<KW>(r32, q * 32 + hi * 16);
;   const unsigned voff = (unsigned)(sr * P.ldv + sc) * 2u, koff = (unsigned)(sr * P.ldk0 + sc) * 2u, koff2 = (unsigned)((tid >> 3) * P.ldk1 + (tid & 7) * 8) * 2u;
;   const int kdst0 = kswz<KW>(sr, sc * 2), kdst2 = kswz<KW>(tid >> 3, 256 + (tid & 7) * 16);
;   struct { bf16x8 vs0, vs1, ks0, ks1, ks2; } sr_[SDEPTH];
;     ...
;     SLOAD(0, 0); VM0(); SWRITE(0, 0); SLOAD(0, 1); WGBAR();
.LBB0_315:
	s_ashr_i32 s36, s33, 4
	s_ashr_i32 s10, s2, 31
	s_add_u32 s2, s2, s26
	s_mul_i32 s7, s36, 0x900
	s_addc_u32 s11, s10, 0
	s_mul_hi_i32 s6, s36, 0x900
	s_add_u32 s10, s2, s7
	s_addc_u32 s11, s11, s6
	s_add_u32 s12, s7, s8
	s_addc_u32 s13, s6, s9
	s_lshl_b64 s[6:7], s[10:11], 11
	s_lshl_b64 s[10:11], s[10:11], 12
	s_add_u32 s9, s15, s10
	s_addc_u32 s10, s16, s11
	s_lshl_b32 s2, s33, 7
	s_and_b32 s2, s2, 0x780
	s_lshl_b32 s35, s2, 1
	s_add_u32 s9, s9, s35
	s_addc_u32 s10, s10, 0
	s_add_u32 s38, s9, s40
	s_addc_u32 s39, s10, s41
	s_lshl_b64 s[12:13], s[12:13], 12
	s_add_u32 s9, s17, s12
	s_addc_u32 s11, s19, s13
	s_add_u32 s10, s9, s35
	s_addc_u32 s11, s11, 0
	v_mov_b32_e32 v176, v184
	v_mov_b32_e32 v2, v1
	v_mov_b32_e32 v3, v1
	v_mov_b32_e32 v4, v1
	v_mov_b32_e32 v5, v1
	v_mov_b32_e32 v6, v1
	v_mov_b32_e32 v7, v1
	v_mov_b32_e32 v8, v1
	v_mov_b32_e32 v9, v1
	v_mov_b32_e32 v10, v1
	v_mov_b32_e32 v11, v1
	v_mov_b32_e32 v12, v1
	v_mov_b32_e32 v13, v1
	v_mov_b32_e32 v14, v1
	v_mov_b32_e32 v15, v1
	s_add_u32 s9, s20, s12
	v_mov_b32_e32 v0, v1
	v_and_b32_e32 v162, 31, v176
	v_mov_b64_e32 v[16:17], v[14:15]
	v_lshlrev_b32_e32 v37, 3, v176
	s_addc_u32 s13, s21, s13
	v_mov_b64_e32 v[14:15], v[12:13]
	v_mov_b64_e32 v[12:13], v[10:11]
	v_mov_b64_e32 v[10:11], v[8:9]
	v_mov_b64_e32 v[8:9], v[6:7]
	v_mov_b64_e32 v[6:7], v[4:5]
	v_mov_b64_e32 v[4:5], v[2:3]
	v_mov_b64_e32 v[2:3], v[0:1]
	v_lshlrev_b32_e32 v0, 12, v162
	v_and_b32_e32 v174, 0x78, v37
	s_add_u32 s12, s9, s35
	v_lshl_add_u64 v[34:35], s[38:39], 0, v[0:1]
	v_ashrrev_i32_e32 v36, 4, v176
	v_lshlrev_b32_e32 v0, 1, v174
	s_addc_u32 s13, s13, 0
	v_lshl_or_b32 v46, v36, 12, v0
	v_mov_b32_e32 v47, v1
	v_lshl_add_u64 v[50:51], s[12:13], 0, v[46:47]
	v_add_co_u32_e32 v18, vcc, s87, v50
	v_lshl_add_u64 v[48:49], s[10:11], 0, v[46:47]
	s_nop 0
	v_addc_co_u32_e32 v19, vcc, 0, v51, vcc
	global_load_dwordx4 v[18:21], v[18:19], off
	s_nop 0
	global_load_dwordx4 v[22:25], v46, s[12:13]
	global_load_dwordx4 v[26:29], v46, s[10:11]
	v_add_co_u32_e32 v30, vcc, s87, v48
	v_bfe_u32 v175, v176, 5, 1
	s_nop 0
	v_addc_co_u32_e32 v31, vcc, 0, v49, vcc
	global_load_dwordx4 v[30:33], v[30:31], off
	v_lshlrev_b32_e32 v164, 4, v175
	v_mov_b32_e32 v165, v1
	v_lshl_add_u64 v[34:35], v[34:35], 0, v[164:165]
	global_load_dwordx4 v[142:145], v[34:35], off
	global_load_dwordx4 v[138:141], v[34:35], off offset:32
	global_load_dwordx4 v[134:137], v[34:35], off offset:64
	global_load_dwordx4 v[130:133], v[34:35], off offset:96
	v_add_co_u32_e32 v252, vcc, s91, v50
	s_nop 1
	v_addc_co_u32_e32 v253, vcc, 0, v51, vcc
	global_load_dwordx4 v[236:239], v[252:253], off
	v_add_co_u32_e32 v252, vcc, s75, v50
	s_nop 1
	v_addc_co_u32_e32 v253, vcc, 0, v51, vcc
	global_load_dwordx4 v[240:243], v[252:253], off
	v_add_co_u32_e32 v252, vcc, s91, v48
	s_nop 1
	v_addc_co_u32_e32 v253, vcc, 0, v49, vcc
	global_load_dwordx4 v[244:247], v[252:253], off
	v_add_co_u32_e32 v252, vcc, s75, v48
	s_nop 1
	v_addc_co_u32_e32 v253, vcc, 0, v49, vcc
	global_load_dwordx4 v[248:251], v[252:253], off
	v_add_co_u32_e32 v252, vcc, s51, v50
	s_nop 1
	v_addc_co_u32_e32 v253, vcc, 0, v51, vcc
	global_load_dwordx4 v[146:149], v[252:253], off
	v_add_co_u32_e32 v252, vcc, s52, v50
	s_nop 1
	v_addc_co_u32_e32 v253, vcc, 0, v51, vcc
	global_load_dwordx4 v[150:153], v[252:253], off
	v_add_co_u32_e32 v252, vcc, s51, v48
	s_nop 1
	v_addc_co_u32_e32 v253, vcc, 0, v49, vcc
	global_load_dwordx4 v[154:157], v[252:253], off
	v_add_co_u32_e32 v252, vcc, s52, v48
	s_nop 1
	v_addc_co_u32_e32 v253, vcc, 0, v49, vcc
	global_load_dwordx4 v[158:161], v[252:253], off
	v_and_b32_e32 v34, 0xfffff0, v36
	v_lshlrev_b32_e32 v35, 1, v36
	v_and_or_b32 v34, v35, 8, v34
	v_lshrrev_b32_e32 v35, 1, v36
	v_and_b32_e32 v38, 3, v36
	v_and_or_b32 v35, v35, 4, v38
	v_add_u32_e32 v38, 32, v36
	v_and_b32_e32 v39, 0xfffff0, v38
	v_lshlrev_b32_e32 v38, 1, v38
	v_and_or_b32 v38, v38, 8, v39
	v_lshrrev_b32_e32 v34, 1, v34
	v_bfe_u32 v37, v37, 5, 2
	v_lshrrev_b32_e32 v38, 1, v38
	v_ashrrev_i32_e32 v165, 8, v176
	v_or_b32_e32 v34, v34, v37
	v_or_b32_e32 v37, v38, v37
	v_lshlrev_b32_e32 v38, 8, v162
	v_lshlrev_b32_e32 v34, 9, v34
	v_lshlrev_b32_e32 v35, 6, v35
	v_lshlrev_b32_e32 v37, 9, v37
	v_lshl_add_u32 v73, v165, 7, v38
	v_and_b32_e32 v38, 48, v0
	v_or3_b32 v192, v34, v35, v38
	v_or3_b32 v193, v37, v35, v38
	v_add_u32_e32 v99, 0, v192
	v_add_u32_e32 v100, 0, v193
	v_lshlrev_b32_e32 v34, 8, v36
	v_and_b32_e32 v35, 0x70, v176
	s_waitcnt vmcnt(0)
	v_bitop3_b32 v194, v0, v34, v35 bitop3:0xde
	v_add_u32_e32 v195, 0, v194
	v_lshlrev_b32_e32 v98, 4, v176
	v_and_b32_e32 v72, 0x70, v98
	v_bitop3_b32 v183, v164, v73, v72 bitop3:0xde
	s_add_i32 s9, 0, 0x18000
	v_and_b32_e32 v177, 63, v176
	s_cmp_lg_u32 0, -1
	s_cselect_b32 s10, 0, 0
	s_lshl_b32 s8, s8, 12
	s_mov_b32 s35, 1
	s_mov_b32 s12, 2
	v_cmp_gt_u32_e64 s[38:39], 32, v177
	v_mov_b32_e32 v180, 0
	v_mov_b32_e32 v199, 1.0
	s_waitcnt vmcnt(6)
	ds_write_b128 v99, v[22:25]
	ds_write_b128 v100, v[18:21]
	v_add_co_u32_e32 v18, vcc, s91, v50
	s_waitcnt vmcnt(5)
	ds_write_b128 v195, v[26:29] offset:49152
	s_waitcnt vmcnt(4)
	ds_write_b128 v195, v[30:33] offset:57344
	v_addc_co_u32_e32 v19, vcc, 0, v51, vcc
	v_add_co_u32_e32 v20, vcc, s75, v50
	s_nop 1
	v_addc_co_u32_e32 v21, vcc, 0, v51, vcc
	s_nop 0
	s_nop 0
	v_add_co_u32_e32 v18, vcc, s91, v48
	s_nop 1
	v_addc_co_u32_e32 v19, vcc, 0, v49, vcc
	v_add_co_u32_e32 v20, vcc, s75, v48
	s_nop 1
	v_addc_co_u32_e32 v21, vcc, 0, v49, vcc
	s_nop 0
	s_nop 0
	s_waitcnt lgkmcnt(0)
	s_barrier
; #define SWRITE(b, i) do { *(bf16x8*)(V_lds + (b) * SHM_V + vst0) = sr_[i].vs0; *(bf16x8*)(V_lds + (b) * SHM_V + vst1) = sr_[i].vs1; \
;     *(bf16x8*)(K_lds + (b) * SHM_K + kdst0) = sr_[i].ks0; *(bf16x8*)(K_lds + (b) * SHM_K + kdst0 + 32 * KW * 2) = sr_[i].ks1; \
;     if constexpr (KW == 192) *(bf16x8*)(K_lds + (b) * SHM_K + kdst2) = sr_[i].ks2; } while (0)
; #define PSM(X0, X1, MN, AL, FIRST) do { if constexpr (DIFF) partialSM_ps<FIRST>(X0, X1, m_reg, AL, negm); else partialSM<DQK>(X0, X1, m_reg, MN, AL); } while (0)
; #define VM0() asm volatile("s_waitcnt vmcnt(0)" ::: "memory")
; #define WGBAR() asm volatile("s_waitcnt lgkmcnt(0)\n\ts_barrier" ::: "memory")
; template <bool FIRST> __device__ __forceinline__ void partialSM_ps(f32x16& p0, f32x16& p1, float& m_reg, float& alpha, f32x16& negm) {
;   float pmax = p0[0];
; #pragma unroll
;   for (int r = 1; r < 16; ++r) pmax = fmaxf(pmax, p0[r]);
; #pragma unroll
;   for (int r = 0; r < 16; ++r) pmax = fmaxf(pmax, p1[r]);
;   { auto rr = __builtin_amdgcn_permlane32_swap(__float_as_uint(pmax), __float_as_uint(pmax), false, false);
;     pmax = fmaxf(__uint_as_float(rr[0]), __uint_as_float(rr[1])); }
;   alpha = 1.f;
;   if (FIRST || !__builtin_expect(__all(pmax <= THRL), 1)) {
;     const float dl = FIRST ? pmax : fmaxf(pmax, 0.f); m_reg += dl;
; #pragma unroll
;     for (int r = 0; r < 16; ++r) { p0[r] -= dl; p1[r] -= dl; }
;     if (!FIRST) alpha = __builtin_amdgcn_exp2f(-dl);
; #pragma unroll
;     for (int r = 0; r < 16; ++r) negm[r] = -m_reg;
;     asm volatile("" : "+v"(negm));
;   }
; #pragma unroll
;   for (int r = 0; r < 16; ++r) p0[r] = __builtin_amdgcn_exp2f(p0[r]);
; template <int DQK, int KW, bool DIFF, int SDEPTH, int QSP, int NBUF>
; __device__ __forceinline__ void attn_unit(const UnitP& P, char* lds) {
;     ...
;     qkt<DQK, KW, QSP>(pA0, pA1, K_lds, kb, qr, qsp, negm); PSM(pA0, pA1, mnA, alA, true);
;     VM0(); SWRITE(1, 0); if (2 < NT) SLOAD(0, 2); WGBAR();
	v_add_u32_e32 v18, 0, v183
	ds_read_b128 v[56:59], v18 offset:49152
	ds_read_b128 v[60:63], v18 offset:57344
	v_or_b32_e32 v18, 32, v164
	v_bitop3_b32 v197, v18, v73, v72 bitop3:0xde
	v_add_u32_e32 v18, 0, v197
	ds_read_b128 v[64:67], v18 offset:49152
	ds_read_b128 v[68:71], v18 offset:57344
	s_waitcnt vmcnt(7) lgkmcnt(0)
	v_mfma_f32_32x32x16_bf16 v[18:33], v[56:59], v[142:145], v[2:17]
	v_or_b32_e32 v56, 64, v164
	v_bitop3_b32 v196, v56, v73, v72 bitop3:0xde
	v_mfma_f32_32x32x16_bf16 v[2:17], v[60:63], v[142:145], v[2:17]
	v_add_u32_e32 v60, 0, v196
	ds_read_b128 v[56:59], v60 offset:49152
	ds_read_b128 v[60:63], v60 offset:57344
	s_waitcnt vmcnt(6)
	v_mfma_f32_32x32x16_bf16 v[18:33], v[64:67], v[138:141], v[18:33]
	v_or_b32_e32 v64, 0x60, v164
	v_bitop3_b32 v198, v64, v73, v72 bitop3:0xde
	v_mfma_f32_32x32x16_bf16 v[2:17], v[68:71], v[138:141], v[2:17]
	v_add_u32_e32 v68, 0, v198
	ds_read_b128 v[64:67], v68 offset:49152
	ds_read_b128 v[68:71], v68 offset:57344
	s_waitcnt vmcnt(5) lgkmcnt(3)
	v_mfma_f32_32x32x16_bf16 v[18:33], v[56:59], v[134:137], v[18:33]
	v_and_b32_e32 v56, 0x3fffffc0, v176
	v_lshl_add_u32 v178, v56, 2, s9
	s_mov_b32 s9, 0
	v_lshl_add_u32 v179, v162, 2, v178
	s_waitcnt lgkmcnt(2)
	v_mfma_f32_32x32x16_bf16 v[2:17], v[60:63], v[134:137], v[2:17]
	s_waitcnt vmcnt(4) lgkmcnt(1)
	v_mfma_f32_32x32x16_bf16 v[18:33], v[64:67], v[130:133], v[18:33]
	s_waitcnt lgkmcnt(0)
	v_mfma_f32_32x32x16_bf16 v[2:17], v[68:71], v[130:133], v[2:17]
	s_nop 9
	v_max_f32_e32 v56, v19, v19
	v_max_f32_e32 v57, v18, v18
	v_max_f32_e32 v56, v57, v56
	v_max3_f32 v56, v56, v20, v21
	v_max3_f32 v56, v56, v22, v23
	v_max3_f32 v56, v56, v24, v25
	v_max3_f32 v56, v56, v26, v27
	v_max3_f32 v56, v56, v28, v29
	v_max3_f32 v56, v56, v30, v31
	v_max3_f32 v56, v56, v32, v33
	v_max3_f32 v56, v56, v2, v3
	v_max3_f32 v56, v56, v4, v5
	v_max3_f32 v56, v56, v6, v7
	v_max3_f32 v56, v56, v8, v9
	v_max3_f32 v56, v56, v10, v11
	v_max3_f32 v56, v56, v12, v13
	v_max3_f32 v56, v56, v14, v15
	v_max3_f32 v56, v56, v16, v17
	v_mov_b32_e32 v57, v56
	s_nop 1
	v_permlane32_swap_b32_e32 v56, v57
	v_max_f32_e32 v57, v57, v57
	v_max_f32_e32 v56, v56, v56
	v_max_f32_e32 v56, v56, v57
	v_add_f32_e32 v182, 0, v56
	v_sub_f32_e32 v96, v16, v56
	v_add_co_u32_e32 v16, vcc, s51, v50
	v_sub_f32_e32 v97, v17, v56
	v_xor_b32_e32 v66, 0x80000000, v182
	v_addc_co_u32_e32 v17, vcc, 0, v51, vcc
	v_sub_f32_e32 v57, v18, v56
	v_mov_b32_e32 v67, v66
	v_mov_b32_e32 v68, v66
	v_mov_b32_e32 v69, v66
	v_mov_b32_e32 v70, v66
	v_mov_b32_e32 v71, v66
	v_mov_b32_e32 v72, v66
	v_mov_b32_e32 v73, v66
	v_mov_b32_e32 v74, v66
	v_mov_b32_e32 v75, v66
	v_mov_b32_e32 v76, v66
	v_mov_b32_e32 v77, v66
	v_mov_b32_e32 v78, v66
	v_mov_b32_e32 v79, v66
	v_mov_b32_e32 v80, v66
	v_mov_b32_e32 v81, v66
	v_add_co_u32_e32 v18, vcc, s52, v50
	v_sub_f32_e32 v58, v19, v56
	s_waitcnt vmcnt(0)
	s_nop 0
	v_addc_co_u32_e32 v19, vcc, 0, v51, vcc
	s_nop 0
	s_nop 0
	v_add_co_u32_e32 v16, vcc, s51, v48
	v_sub_f32_e32 v20, v20, v56
	s_nop 0
	v_addc_co_u32_e32 v17, vcc, 0, v49, vcc
	v_add_co_u32_e32 v18, vcc, s52, v48
	v_lshlrev_b32_e32 v48, 1, v176
	s_nop 0
	v_addc_co_u32_e32 v19, vcc, 0, v49, vcc
	s_nop 0
	s_nop 0
	v_lshlrev_b32_e32 v18, 3, v177
	v_and_b32_e32 v19, 0xc0, v98
	v_and_or_b32 v19, v18, 24, v19
	v_and_b32_e32 v48, 32, v48
	v_and_b32_e32 v18, 0x100, v18
	v_or3_b32 v18, v19, v48, v18
	v_add_u32_e32 v181, s10, v18
	s_mul_hi_i32 s10, s36, 0x900000
	s_mul_i32 s36, s36, 0x900000
	s_add_u32 s8, s36, s8
	s_addc_u32 s11, s10, 0
	s_and_b32 s10, s33, 15
	s_lshl_b32 s10, s10, 8
	v_sub_f32_e32 v21, v21, v56
	v_sub_f32_e32 v22, v22, v56
	v_sub_f32_e32 v23, v23, v56
	v_sub_f32_e32 v24, v24, v56
	v_sub_f32_e32 v25, v25, v56
	v_sub_f32_e32 v26, v26, v56
	v_sub_f32_e32 v27, v27, v56
	v_sub_f32_e32 v28, v28, v56
	v_sub_f32_e32 v29, v29, v56
	v_sub_f32_e32 v30, v30, v56
	v_sub_f32_e32 v31, v31, v56
	v_sub_f32_e32 v32, v32, v56
	v_sub_f32_e32 v33, v33, v56
	v_add_u32_e32 v18, 0x10000, v195
	s_or_b32 s8, s8, s10
	v_exp_f32_e32 v219, v57
	v_exp_f32_e32 v221, v58
	v_exp_f32_e32 v217, v20
	v_exp_f32_e32 v220, v21
	v_exp_f32_e32 v215, v22
	v_exp_f32_e32 v218, v23
	v_exp_f32_e32 v214, v24
	v_exp_f32_e32 v216, v25
	v_exp_f32_e32 v211, v26
	v_exp_f32_e32 v213, v27
	v_exp_f32_e32 v209, v28
	v_exp_f32_e32 v212, v29
	v_exp_f32_e32 v207, v30
	v_exp_f32_e32 v210, v31
	v_exp_f32_e32 v206, v32
	v_exp_f32_e32 v208, v33
	s_waitcnt vmcnt(7)
	ds_write_b128 v99, v[236:239] offset:16384
	s_waitcnt vmcnt(6)
	ds_write_b128 v100, v[240:243] offset:16384
	s_waitcnt vmcnt(5)
	ds_write_b128 v18, v[244:247]
	s_waitcnt vmcnt(4)
	ds_write_b128 v18, v[248:251] offset:8192
	s_add_u32 s10, s27, s8
	v_mov_b32_e32 v16, v1
	v_mov_b32_e32 v17, v1
	s_waitcnt lgkmcnt(0)
	s_barrier
	s_addc_u32 s11, s28, s11
	v_sub_f32_e32 v95, v15, v56
	v_sub_f32_e32 v94, v14, v56
	v_sub_f32_e32 v93, v13, v56
	v_sub_f32_e32 v92, v12, v56
	v_sub_f32_e32 v91, v11, v56
	v_sub_f32_e32 v90, v10, v56
	v_sub_f32_e32 v89, v9, v56
	v_sub_f32_e32 v88, v8, v56
	v_sub_f32_e32 v87, v7, v56
	v_sub_f32_e32 v86, v6, v56
	v_sub_f32_e32 v85, v5, v56
	v_sub_f32_e32 v84, v4, v56
	v_sub_f32_e32 v83, v3, v56
	v_sub_f32_e32 v82, v2, v56
	v_mov_b32_e32 v2, v1
	v_mov_b32_e32 v3, v1
	v_mov_b32_e32 v4, v1
	v_mov_b32_e32 v5, v1
	v_mov_b32_e32 v6, v1
	v_mov_b32_e32 v7, v1
	v_mov_b32_e32 v8, v1
	v_mov_b32_e32 v9, v1
	v_mov_b32_e32 v10, v1
	v_mov_b32_e32 v11, v1
	v_mov_b32_e32 v12, v1
	v_mov_b32_e32 v13, v1
	v_mov_b32_e32 v14, v1
	v_mov_b32_e32 v15, v1
	v_lshl_add_u64 v[166:167], s[10:11], 0, v[46:47]
	v_mov_b64_e32 v[64:65], v[16:17]
	v_mov_b64_e32 v[48:49], v[16:17]
	v_mov_b64_e32 v[32:33], v[16:17]
	v_mov_b64_e32 v[62:63], v[14:15]
	v_mov_b64_e32 v[60:61], v[12:13]
	v_mov_b64_e32 v[58:59], v[10:11]
	v_mov_b64_e32 v[56:57], v[8:9]
	v_mov_b64_e32 v[54:55], v[6:7]
	v_mov_b64_e32 v[52:53], v[4:5]
	v_mov_b64_e32 v[50:51], v[2:3]
	v_mov_b64_e32 v[46:47], v[14:15]
	v_mov_b64_e32 v[44:45], v[12:13]
	v_mov_b64_e32 v[42:43], v[10:11]
	v_mov_b64_e32 v[40:41], v[8:9]
	v_mov_b64_e32 v[38:39], v[6:7]
	v_mov_b64_e32 v[36:37], v[4:5]
	v_mov_b64_e32 v[34:35], v[2:3]
	v_mov_b64_e32 v[30:31], v[14:15]
	v_mov_b64_e32 v[28:29], v[12:13]
	v_mov_b64_e32 v[26:27], v[10:11]
	v_mov_b64_e32 v[24:25], v[8:9]
	v_mov_b64_e32 v[22:23], v[6:7]
	v_mov_b64_e32 v[20:21], v[4:5]
	v_mov_b64_e32 v[18:19], v[2:3]
